# strategy 7.2 (wait at first consumer): the forgetting-attention unit's prologue loop issues its two independent loads together and waits once
# speedup vs baseline: 1.0086x; 1.0017x over previous
; template <int MODE>
; __device__ void attn_unit(unsigned char* lds, int b, int qb, const bf16_t* Qp, const bf16_t* Kp, const bf16_t* Vp, int ld, bf16_t* Op, int ldo, const float* Fbh, const float* reltab, const float* knsuf, const unsigned* fflag, unsigned fval) {
;     ...
;     const int nt = kt1 - kt0 + 1;
;     if (MODE == 0) { for (int i = tid; i <= kt1; i += NTHR) { ktab[i] = knsuf[i]; ftab[i] = (Fref - Fbh[64 * i + 63]) * LOG2E; } }
.LBB0_188:
	global_load_dword v3, v[4:5], off
	v_add_u32_e32 v10, 0x200, v10
	v_cmp_gt_i32_e32 vcc, v10, v7
	v_lshl_add_u64 v[4:5], v[4:5], 0, s[94:95]
	s_or_b64 s[2:3], vcc, s[2:3]
	v_mov_b32_e32 v12, v2
	v_ashrrev_i32_e32 v13, 31, v2
	v_lshl_add_u64 v[12:13], v[12:13], 2, v[148:149]
	global_load_dword v252, v[12:13], off offset:252
	v_add_u32_e32 v2, 0x8000, v2
	s_waitcnt vmcnt(0) lgkmcnt(0)
	ds_write_b32 v9, v3
	v_sub_f32_e32 v3, v181, v252
	v_mul_f32_e32 v3, 0x3fb8aa3b, v3
	ds_write_b32 v9, v3 offset:512
	v_add_u32_e32 v9, 0x800, v9
	s_andn2_b64 exec, exec, s[2:3]
	s_cbranch_execnz .LBB0_188
